# layer-0 load rebalance across the fused out-proj/rmsnorm seam: the 32 blocks owning a second G tile skip phase A', the other 224 blocks take their rows (plus K LDS row stride 224 in attention)
# speedup vs baseline: 1.0279x; 1.0279x over previous
; #define LAS __attribute__((address_space(3)))
; __device__ __forceinline__ int opaque_tid() { int t; asm volatile("v_mov_b32 %0, %1" : "=v"(t) : "v"((int)threadIdx.x)); return t; }
; #define ATT_LOAD(S_, tt) do { const bf16_t* kt_ = kg + (size_t)(tt) * 64 * 96; rk0[S_] = ld8(kt_ + kp0 * 8); if (kp1 < 768) rk1[S_] = ld8(kt_ + kp1 * 8); rv[S_] = ld8(vg + (size_t)vd * NKEY + (tt) * 64 + vpart * 8); } while (0)
; #define ATT_STORE(S_, bufi) do { LAS unsigned char* kb_ = lds + (bufi) * KBUF; *(LAS u32x4*)(kb_ + (kp0 / 12) * KST + (kp0 % 12) * 16) = rk0[S_]; if (kp1 < 768) *(LAS u32x4*)(kb_ + (kp1 / 12) * KST + (kp1 % 12) * 16) = rk1[S_]; \
;         *(LAS u32x4*)(lds + VOFF + (bufi) * VBUF + vd * VST + vpart * 16) = rv[S_]; } while (0)
; __device__ __forceinline__ void attn_unit(LAS unsigned char* lds, const bf16_t* QB, const bf16_t* KB, const bf16_t* VT, const bf16_t* P, bf16_t* Z0, int b, int h, int qrow0, int nkeys) {
;     const int tid = opaque_tid(), lane = tid & 63, wave = tid >> 6, fr = lane & 15, fq = lane >> 4;
;     constexpr int KST = 208, VST = 144, KBUF = 64 * KST, VBUF = 64 * VST, VOFF = 2 * KBUF;
;     bf16x8 qf[2][3];
; #pragma unroll
;     for (int qb = 0; qb < 2; ++qb)
; #pragma unroll
;         for (int ks = 0; ks < 3; ++ks) qf[qb][ks] = asfrag(ld8(QB + (size_t)(qrow0 + wave * 32 + qb * 16 + fr) * 384 + h * 96 + ks * 32 + fq * 8));
;     const bf16_t* kg = KB + (size_t)(b * 4 + h) * NKEY * 96;
;     const bf16_t* vg = VT + (size_t)(b * 4 + h) * 64 * NKEY;
;     const int kp0 = tid, kp1 = tid + 512;
;     const int vd = tid >> 3, vpart = tid & 7;
;     u32x4 rk0[2], rk1[2], rv[2];
;     const int ntile = nkeys >> 6;
;     ...
;     __syncthreads();
;     ATT_LOAD(0, 0); ATT_STORE(0, 0);
;     __syncthreads();
; __global__ void __launch_bounds__(512, 2) fwd_kernel(KArgs a) {
;     ...
;             for (int u = bid; u < 256 + (wctx ? 32 : 0); u += G) {
;                 if (u < 256) { const int us = G == 256 ? (u & 7) * 32 + (u >> 3) : u;
;                     const int qb = us & 7, h = (us >> 3) & 3, b = us >> 5; attn_unit(lds, QB, KB, VT, P, Z0, b, h, b * 2048 + qb * 256, NKEY); }
.LBB0_1036:
	s_movk_i32 s18, 0xe0
	s_and_b64 vcc, exec, s[4:5]
	s_cbranch_vccz .LBB0_1009
	s_lshl_b32 s1, s46, 5
	s_and_b32 s1, s1, 0xe0
	s_ashr_i32 s4, s46, 3
	s_add_i32 s1, s1, s4
	v_readlane_b32 s4, v253, 25
	v_readlane_b32 s5, v253, 26
	s_and_b64 s[4:5], s[4:5], exec
	s_cselect_b32 s4, s1, s46
	s_bfe_u32 s1, s4, 0x20003
	s_ashr_i32 s6, s4, 5
	s_lshl_b32 s4, s4, 8
	s_lshl_b32 s5, s6, 11
	s_and_b32 s4, s4, 0x700
	s_or_b32 s4, s5, s4
	v_mov_b32 v29, v194
	v_mov_b32_e32 v6, v1
	v_and_b32_e32 v32, 15, v29
	v_ashrrev_i32_e32 v0, 1, v29
	v_or_b32_e32 v2, s4, v32
	s_mul_i32 s4, s1, 0xc0
	v_bfe_u32 v170, v29, 4, 2
	v_and_b32_e32 v0, 0xffffffe0, v0
	s_add_u32 s4, s28, s4
	v_add_u32_e32 v90, v2, v0
	s_addc_u32 s5, s29, 0
	v_lshlrev_b32_e32 v0, 4, v170
	v_lshl_add_u64 v[2:3], s[4:5], 0, v[0:1]
	v_or_b32_e32 v86, 16, v90
	v_mad_i64_i32 v[4:5], s[4:5], v90, s50, v[2:3]
	v_mad_i64_i32 v[2:3], s[4:5], v86, s50, v[2:3]
	s_lshl_b32 s4, s6, 2
	s_or_b32 s6, s4, s1
	s_mul_i32 s4, s6, 0x6c000
	s_mul_hi_i32 s5, s6, 0x6c000
	s_add_u32 s22, s30, s4
	v_lshlrev_b32_e32 v26, 3, v29
	flat_load_dwordx4 v[34:37], v[4:5]
	flat_load_dwordx4 v[38:41], v[4:5] offset:64
	flat_load_dwordx4 v[42:45], v[4:5] offset:128
	flat_load_dwordx4 v[46:49], v[2:3]
	flat_load_dwordx4 v[50:53], v[2:3] offset:64
	flat_load_dwordx4 v[54:57], v[2:3] offset:128
	s_addc_u32 s23, s31, s5
	v_ashrrev_i32_e32 v27, 31, v26
	v_lshl_add_u64 v[2:3], v[26:27], 1, s[22:23]
	s_waitcnt lgkmcnt(0)
	s_barrier
	flat_load_dwordx4 v[14:17], v[2:3]
	v_mov_b32_e32 v2, v1
	v_mov_b32_e32 v3, v1
	v_mov_b32_e32 v4, v1
	v_mov_b32_e32 v5, v1
	v_mov_b32_e32 v7, v1
	v_add_u32_e32 v33, 0x200, v29
	s_movk_i32 s7, 0xff
	v_mov_b32_e32 v0, v1
	v_mov_b64_e32 v[8:9], v[6:7]
	v_cmp_lt_i32_e32 vcc, s7, v29
	v_cmp_gt_i32_e64 s[36:37], s14, v29
	v_mov_b32_e32 v18, 0
	v_lshlrev_b32_e32 v28, 3, v33
	v_mov_b64_e32 v[6:7], v[4:5]
	v_mov_b64_e32 v[4:5], v[2:3]
	v_mov_b64_e32 v[2:3], v[0:1]
	v_mov_b32_e32 v19, 0
	v_mov_b32_e32 v20, 0
	v_mov_b32_e32 v21, 0
	s_and_saveexec_b64 s[20:21], s[36:37]
	s_cbranch_execz .LBB0_1039
	v_lshlrev_b32_e32 v2, 3, v33
	v_ashrrev_i32_e32 v3, 31, v2
	v_lshl_add_u64 v[2:3], v[2:3], 1, s[22:23]
	flat_load_dwordx4 v[2:5], v[2:3]
	v_mov_b32_e32 v6, v1
	v_mov_b32_e32 v7, v1
	v_mov_b32_e32 v8, v1
	v_mov_b32_e32 v9, v1
	s_waitcnt vmcnt(0) lgkmcnt(0)
	v_mov_b32_e32 v18, v2
	v_mov_b32_e32 v19, v3
	v_mov_b32_e32 v20, v4
	v_mov_b32_e32 v21, v5
.LBB0_1039:
	s_or_b64 exec, exec, s[20:21]
	s_mul_i32 s20, s6, 0x48000
	s_mul_hi_i32 s21, s6, 0x48000
	s_add_u32 s6, s34, s20
	s_addc_u32 s7, s35, s21
	v_ashrrev_i32_e32 v58, 3, v29
	v_and_b32_e32 v0, 7, v29
	v_mov_b64_e32 v[22:23], s[6:7]
	v_mad_i64_i32 v[22:23], s[6:7], v58, s88, v[22:23]
	v_lshlrev_b32_e32 v0, 4, v0
	v_lshl_add_u64 v[30:31], v[22:23], 0, v[0:1]
	flat_load_dwordx4 v[22:25], v[30:31]
	s_mov_b32 s6, 0x2aaaaaab
	v_mul_hi_i32 v59, v29, s6
	v_lshrrev_b32_e32 v60, 31, v59
	v_ashrrev_i32_e32 v59, 1, v59
	v_add_u32_e32 v59, v59, v60
	v_mul_lo_u32 v60, v59, s18
	v_mul_lo_u32 v59, v59, 12
	v_sub_u32_e32 v29, v29, v59
	v_add_u32_e32 v60, 0, v60
	v_lshlrev_b32_e32 v29, 4, v29
	v_add_u32_e32 v171, v60, v29
	s_waitcnt vmcnt(0) lgkmcnt(0)
	ds_write_b128 v171, v[14:17]
	v_mul_hi_i32 v15, v33, s6
	v_lshrrev_b32_e32 v14, 31, v15
	v_ashrrev_i32_e32 v15, 1, v15
	s_and_saveexec_b64 s[24:25], s[36:37]
	s_cbranch_execz .LBB0_1041
	v_add_u32_e32 v16, v15, v14
	v_mul_lo_u32 v17, v16, s18
	v_mul_lo_u32 v16, v16, 12
	v_sub_u32_e32 v16, v33, v16
	v_lshlrev_b32_e32 v16, 4, v16
	v_add3_u32 v16, 0, v17, v16
	ds_write_b128 v16, v[18:21]
.LBB0_1041:
	s_or_b64 exec, exec, s[24:25]
	v_mul_lo_u32 v16, v58, s15
	s_add_u32 s24, s22, 0x3000
	v_add_u32_e32 v16, 0, v16
	s_addc_u32 s25, s23, 0
	v_add_u32_e32 v172, v16, v0
	v_lshl_add_u64 v[16:17], v[26:27], 1, s[24:25]
	ds_write_b128 v172, v[22:25] offset:28672
	s_waitcnt lgkmcnt(0)
	s_barrier
	global_load_dwordx4 v[62:65], v[16:17], off
	s_and_saveexec_b64 s[6:7], vcc
	s_xor_b64 s[26:27], exec, s[6:7]
	v_lshlrev_b32_e32 v28, 3, v33
	s_andn2_saveexec_b64 s[26:27], s[26:27]
	s_cbranch_execz .LBB0_1045
	v_ashrrev_i32_e32 v29, 31, v28
	v_lshl_add_u64 v[2:3], v[28:29], 1, s[24:25]
	global_load_dwordx4 v[2:5], v[2:3], off

; #define ATT_LOAD(S_, tt) do { const bf16_t* kt_ = kg + (size_t)(tt) * 64 * 96; rk0[S_] = ld8(kt_ + kp0 * 8); if (kp1 < 768) rk1[S_] = ld8(kt_ + kp1 * 8); rv[S_] = ld8(vg + (size_t)vd * NKEY + (tt) * 64 + vpart * 8); } while (0)
; #define ATT_STORE(S_, bufi) do { LAS unsigned char* kb_ = lds + (bufi) * KBUF; *(LAS u32x4*)(kb_ + (kp0 / 12) * KST + (kp0 % 12) * 16) = rk0[S_]; if (kp1 < 768) *(LAS u32x4*)(kb_ + (kp1 / 12) * KST + (kp1 % 12) * 16) = rk1[S_]; \
;         *(LAS u32x4*)(lds + VOFF + (bufi) * VBUF + vd * VST + vpart * 16) = rv[S_]; } while (0)
; __device__ __forceinline__ void attn_unit(LAS unsigned char* lds, const bf16_t* QB, const bf16_t* KB, const bf16_t* VT, const bf16_t* P, bf16_t* Z0, int b, int h, int qrow0, int nkeys) {
;     ...
;     const bf16_t* kg = KB + (size_t)(b * 4 + h) * NKEY * 96;
;     const bf16_t* vg = VT + (size_t)(b * 4 + h) * 64 * NKEY;
;     const int kp0 = tid, kp1 = tid + 512;
;     const int vd = tid >> 3, vpart = tid & 7;
;     u32x4 rk0[2], rk1[2], rv[2];
;     const int ntile = nkeys >> 6;
;     ...
;     __syncthreads();
;     ATT_LOAD(0, 0); ATT_STORE(0, 0);
;     __syncthreads();
;     if (1 < ntile) ATT_LOAD(0, 1);
;     if (2 < ntile) ATT_LOAD(1, 2);
;     f32x4 o[2][4]; float lsum[2];
; #pragma unroll
;     for (int qb = 0; qb < 2; ++qb) { lsum[qb] = 0.f;
; #pragma unroll
;         for (int db = 0; db < 4; ++db) o[qb][db] = (f32x4){0.f, 0.f, 0.f, 0.f}; }
.LBB0_1049:
	s_or_b64 exec, exec, s[24:25]
	global_load_dwordx4 v[78:81], v[30:31], off offset:256
	v_add_u32_e32 v14, v15, v14
	v_mul_lo_u32 v15, v14, s18
	v_mul_lo_u32 v14, v14, 12
	v_mad_i64_i32 v[16:17], s[6:7], v58, s88, 0
	v_sub_u32_e32 v14, v33, v14
	v_lshlrev_b32_e32 v18, 3, v170
	v_lshl_add_u32 v19, v170, 4, 0
	v_lshlrev_b32_e32 v173, 4, v14
	v_add_u32_e32 v174, 0, v15
	v_lshl_add_u64 v[14:15], s[20:21], 0, v[16:17]
	v_sub_u32_e32 v18, v19, v18
	v_mul_u32_u24_e32 v20, 0xe0, v32
	v_mul_u32_u24_e32 v21, 0x90, v32
	v_lshl_add_u64 v[96:97], v[14:15], 0, v[0:1]
	v_mov_b32_e32 v14, 0
	v_ashrrev_i32_e32 v91, 31, v90
	v_ashrrev_i32_e32 v87, 31, v86
	v_lshl_add_u64 v[92:93], v[28:29], 1, s[4:5]
	v_lshl_add_u64 v[94:95], v[26:27], 1, s[4:5]
	s_mov_b32 s6, 0
	v_add_u32_e32 v0, v19, v20
	v_add_u32_e32 v175, v18, v21
	v_mov_b32_e32 v15, v14
	v_mov_b32_e32 v16, v14
	v_mov_b32_e32 v17, v14
	v_mov_b32_e32 v18, v14
	v_mov_b32_e32 v19, v14
	v_mov_b32_e32 v20, v14
	v_mov_b32_e32 v21, v14
	v_mov_b32_e32 v22, v14
	v_mov_b32_e32 v23, v14
	v_mov_b32_e32 v24, v14
	v_mov_b32_e32 v25, v14
	v_mov_b32_e32 v26, v14
	v_mov_b32_e32 v27, v14
	v_mov_b32_e32 v28, v14
	v_mov_b32_e32 v29, v14
	v_mov_b32_e32 v30, v14
	v_mov_b32_e32 v31, v14
	v_mov_b32_e32 v32, v14
	v_mov_b32_e32 v33, v14
	v_mov_b32_e32 v58, v14
	v_mov_b32_e32 v59, v14
	v_mov_b32_e32 v60, v14
	v_mov_b32_e32 v61, v14
	v_mov_b32_e32 v74, v14
	v_mov_b32_e32 v75, v14
	v_mov_b32_e32 v76, v14
	v_mov_b32_e32 v77, v14
	v_mov_b32_e32 v82, v14
	v_mov_b32_e32 v83, v14
	v_mov_b32_e32 v84, v14
	v_mov_b32_e32 v85, v14
	v_mov_b32_e32 v88, v14
	v_mov_b32_e32 v89, v14
	s_branch .LBB0_1052

; #define LAS __attribute__((address_space(3)))
; #define MFMA16(a, b, c) __builtin_amdgcn_mfma_f32_16x16x32_bf16((a), (b), (c), 0, 0, 0)
; __device__ __forceinline__ void attn_unit(LAS unsigned char* lds, const bf16_t* QB, const bf16_t* KB, const bf16_t* VT, const bf16_t* P, bf16_t* Z0, int b, int h, int qrow0, int nkeys) {
;     ...
;     for (int t2 = 0; t2 < ntile; t2 += 2) {
; #pragma unroll
;       for (int half = 0; half < 2; ++half) { const int tt = t2 + half; if (tt < ntile) {
;         const int cur = half;
;         const LAS unsigned char* kb = lds + cur * KBUF; const LAS unsigned char* vb = lds + VOFF + cur * VBUF;
;         f32x4 s[2][4];
; #pragma unroll
;         for (int kbk = 0; kbk < 4; ++kbk) { s[0][kbk] = (f32x4){0.f, 0.f, 0.f, 0.f}; s[1][kbk] = s[0][kbk];
; #pragma unroll
;             for (int ks = 0; ks < 3; ++ks) { const bf16x8 kf = *(const LAS bf16x8*)(kb + (kbk * 16 + fr) * KST + ks * 64 + fq * 16);
;                 s[0][kbk] = MFMA16(kf, qf[0][ks], s[0][kbk]); s[1][kbk] = MFMA16(kf, qf[1][ks], s[1][kbk]); } }
;         bf16x8 pf[2][2];
; #pragma unroll
;         for (int qb = 0; qb < 2; ++qb) {
;             float ps = 0.f;
; #pragma unroll
;             for (int kbk = 0; kbk < 4; ++kbk)
; #pragma unroll
;                 for (int q = 0; q < 4; ++q) { const float pv = __builtin_amdgcn_exp2f(s[qb][kbk][q]); s[qb][kbk][q] = pv; ps += pv; }
;             lsum[qb] += ps;
; #pragma unroll
;             for (int k2 = 0; k2 < 2; ++k2) { u32x4 w; w.x = cvt_pk_bf16(s[qb][2 * k2][0], s[qb][2 * k2][1]); w.y = cvt_pk_bf16(s[qb][2 * k2][2], s[qb][2 * k2][3]);
;                 w.z = cvt_pk_bf16(s[qb][2 * k2 + 1][0], s[qb][2 * k2 + 1][1]); w.w = cvt_pk_bf16(s[qb][2 * k2 + 1][2], s[qb][2 * k2 + 1][3]); pf[qb][k2] = asfrag(w); }
;         }
; #pragma unroll
;         for (int db = 0; db < 4; ++db)
; #pragma unroll
;             for (int k2 = 0; k2 < 2; ++k2) { const LAS unsigned char* vp = vb + (db * 16 + fr) * VST + (k2 * 32 + fq * 4) * 2;
;                 const u32x2 lo = *(const LAS u32x2*)vp, hi = *(const LAS u32x2*)(vp + 32);
;                 const bf16x8 vf = asfrag((u32x4){lo.x, lo.y, hi.x, hi.y});
;                 o[0][db] = MFMA16(vf, pf[0][k2], o[0][db]); o[1][db] = MFMA16(vf, pf[1][k2], o[1][db]); }
;         if (tt + 1 < ntile) ATT_STORE(half, cur ^ 1);
;         __syncthreads();
;         if (tt + 3 < ntile) ATT_LOAD(half, tt + 3);
.Lmy_att_noprio:
.Lmy_att_loop:
	ds_read_b128 v[132:135], v0 offset:0
	ds_read_b128 v[136:139], v0 offset:64
	ds_read_b128 v[140:143], v0 offset:128
	ds_read_b128 v[156:159], v0 offset:3584
	ds_read_b128 v[160:163], v0 offset:3648
	ds_read_b128 v[164:167], v0 offset:3712
	ds_read_b128 v[238:241], v0 offset:7168
	ds_read_b128 v[242:245], v0 offset:7232
	ds_read_b128 v[246:249], v0 offset:7296
	s_waitcnt lgkmcnt(6)
	v_mfma_f32_16x16x32_bf16 v[100:103], v[132:135], v[34:37], 0
	v_mfma_f32_16x16x32_bf16 v[116:119], v[132:135], v[46:49], 0
	v_mfma_f32_16x16x32_bf16 v[100:103], v[136:139], v[38:41], v[100:103]
	v_mfma_f32_16x16x32_bf16 v[116:119], v[136:139], v[50:53], v[116:119]
	v_mfma_f32_16x16x32_bf16 v[100:103], v[140:143], v[42:45], v[100:103]
	v_mfma_f32_16x16x32_bf16 v[116:119], v[140:143], v[54:57], v[116:119]
	ds_read_b128 v[132:135], v0 offset:10752
	ds_read_b128 v[136:139], v0 offset:10816
	ds_read_b128 v[140:143], v0 offset:10880
	s_waitcnt lgkmcnt(6)
	v_mfma_f32_16x16x32_bf16 v[104:107], v[156:159], v[34:37], 0
	v_mfma_f32_16x16x32_bf16 v[120:123], v[156:159], v[46:49], 0
	v_mfma_f32_16x16x32_bf16 v[104:107], v[160:163], v[38:41], v[104:107]
	v_mfma_f32_16x16x32_bf16 v[120:123], v[160:163], v[50:53], v[120:123]
	v_mfma_f32_16x16x32_bf16 v[104:107], v[164:167], v[42:45], v[104:107]
	v_mfma_f32_16x16x32_bf16 v[120:123], v[164:167], v[54:57], v[120:123]
	ds_read_b64 v[156:157], v175 offset:28672
	ds_read_b64 v[158:159], v175 offset:28704
	ds_read_b64 v[160:161], v175 offset:30976
	ds_read_b64 v[162:163], v175 offset:31008
	ds_read_b64 v[164:165], v175 offset:33280
	ds_read_b64 v[166:167], v175 offset:33312
	s_waitcnt lgkmcnt(9)
	v_mfma_f32_16x16x32_bf16 v[108:111], v[238:241], v[34:37], 0
	v_exp_f32_e32 v100, v100
	v_exp_f32_e32 v101, v101
	v_exp_f32_e32 v102, v102
	v_exp_f32_e32 v103, v103
	v_mfma_f32_16x16x32_bf16 v[124:127], v[238:241], v[46:49], 0
	v_exp_f32_e32 v116, v116
	v_exp_f32_e32 v117, v117
	v_exp_f32_e32 v118, v118
	v_exp_f32_e32 v119, v119
	v_mfma_f32_16x16x32_bf16 v[108:111], v[242:245], v[38:41], v[108:111]
	v_add_f32_e32 v98, v98, v100
	v_add_f32_e32 v99, v99, v101
	v_cvt_pk_bf16_f32 v176, v100, v101
	v_mfma_f32_16x16x32_bf16 v[124:127], v[242:245], v[50:53], v[124:127]
	v_add_f32_e32 v98, v98, v102
	v_add_f32_e32 v99, v99, v103
	v_cvt_pk_bf16_f32 v177, v102, v103
	v_mfma_f32_16x16x32_bf16 v[108:111], v[246:249], v[42:45], v[108:111]
	v_add_f32_e32 v192, v192, v116
	v_add_f32_e32 v193, v193, v117
	v_cvt_pk_bf16_f32 v184, v116, v117
	v_mfma_f32_16x16x32_bf16 v[124:127], v[246:249], v[54:57], v[124:127]
	v_add_f32_e32 v192, v192, v118
	v_add_f32_e32 v193, v193, v119
	v_cvt_pk_bf16_f32 v185, v118, v119
	ds_read_b64 v[238:239], v175 offset:35584
	ds_read_b64 v[240:241], v175 offset:35616
	ds_read_b64 v[242:243], v175 offset:28736
	ds_read_b64 v[244:245], v175 offset:28768
	ds_read_b64 v[246:247], v175 offset:31040
	ds_read_b64 v[248:249], v175 offset:31072
	s_waitcnt lgkmcnt(12)
	v_mfma_f32_16x16x32_bf16 v[112:115], v[132:135], v[34:37], 0
	v_exp_f32_e32 v104, v104
	v_exp_f32_e32 v105, v105
	v_exp_f32_e32 v106, v106
	v_exp_f32_e32 v107, v107
	v_mfma_f32_16x16x32_bf16 v[128:131], v[132:135], v[46:49], 0
	v_exp_f32_e32 v120, v120
	v_exp_f32_e32 v121, v121
	v_exp_f32_e32 v122, v122
	v_exp_f32_e32 v123, v123
	v_mfma_f32_16x16x32_bf16 v[112:115], v[136:139], v[38:41], v[112:115]
	v_add_f32_e32 v98, v98, v104
	v_add_f32_e32 v99, v99, v105
	v_cvt_pk_bf16_f32 v178, v104, v105
	v_mfma_f32_16x16x32_bf16 v[128:131], v[136:139], v[50:53], v[128:131]
	v_add_f32_e32 v98, v98, v106
	v_add_f32_e32 v99, v99, v107
	v_cvt_pk_bf16_f32 v179, v106, v107
	v_mfma_f32_16x16x32_bf16 v[112:115], v[140:143], v[42:45], v[112:115]
	v_add_f32_e32 v192, v192, v120
	v_add_f32_e32 v193, v193, v121
	v_cvt_pk_bf16_f32 v186, v120, v121
	v_mfma_f32_16x16x32_bf16 v[128:131], v[140:143], v[54:57], v[128:131]
	v_add_f32_e32 v192, v192, v122
	v_add_f32_e32 v193, v193, v123
	v_cvt_pk_bf16_f32 v187, v122, v123
	s_waitcnt lgkmcnt(6)
	ds_read_b64 v[132:133], v175 offset:33344
	ds_read_b64 v[134:135], v175 offset:33376
	ds_read_b64 v[136:137], v175 offset:35648
	ds_read_b64 v[138:139], v175 offset:35680
	v_mfma_f32_16x16x32_bf16 v[82:85], v[156:159], v[176:179], v[82:85]
	v_exp_f32_e32 v108, v108
	v_exp_f32_e32 v109, v109
	v_exp_f32_e32 v110, v110
	v_exp_f32_e32 v111, v111
	v_exp_f32_e32 v124, v124
	v_mfma_f32_16x16x32_bf16 v[26:29], v[156:159], v[184:187], v[26:29]
	v_exp_f32_e32 v125, v125
	v_exp_f32_e32 v126, v126
	v_exp_f32_e32 v127, v127
	v_add_f32_e32 v98, v98, v108
	v_add_f32_e32 v99, v99, v109
	v_mfma_f32_16x16x32_bf16 v[74:77], v[160:163], v[176:179], v[74:77]
	v_cvt_pk_bf16_f32 v180, v108, v109
	v_add_f32_e32 v98, v98, v110
	v_add_f32_e32 v99, v99, v111
	v_cvt_pk_bf16_f32 v181, v110, v111
	v_add_f32_e32 v192, v192, v124
	v_mfma_f32_16x16x32_bf16 v[22:25], v[160:163], v[184:187], v[22:25]
	v_add_f32_e32 v193, v193, v125
	v_cvt_pk_bf16_f32 v188, v124, v125
	v_add_f32_e32 v192, v192, v126
	v_add_f32_e32 v193, v193, v127
	v_cvt_pk_bf16_f32 v189, v126, v127
	v_mfma_f32_16x16x32_bf16 v[58:61], v[164:167], v[176:179], v[58:61]
	v_exp_f32_e32 v112, v112
	v_exp_f32_e32 v113, v113
	v_exp_f32_e32 v114, v114
	v_exp_f32_e32 v115, v115
	v_exp_f32_e32 v128, v128
	v_mfma_f32_16x16x32_bf16 v[18:21], v[164:167], v[184:187], v[18:21]
	v_exp_f32_e32 v129, v129
	v_exp_f32_e32 v130, v130
	v_exp_f32_e32 v131, v131
	v_add_f32_e32 v98, v98, v112
	v_add_f32_e32 v99, v99, v113
	s_waitcnt lgkmcnt(8)
	v_mfma_f32_16x16x32_bf16 v[30:33], v[238:241], v[176:179], v[30:33]
	v_cvt_pk_bf16_f32 v182, v112, v113
	v_add_f32_e32 v98, v98, v114
	v_add_f32_e32 v99, v99, v115
	v_cvt_pk_bf16_f32 v183, v114, v115
	v_add_f32_e32 v192, v192, v128
	v_mfma_f32_16x16x32_bf16 v[14:17], v[238:241], v[184:187], v[14:17]
	v_add_f32_e32 v193, v193, v129
	v_cvt_pk_bf16_f32 v190, v128, v129
	v_add_f32_e32 v192, v192, v130
	v_add_f32_e32 v193, v193, v131
	v_cvt_pk_bf16_f32 v191, v130, v131
	s_waitcnt lgkmcnt(0)
	v_mfma_f32_16x16x32_bf16 v[82:85], v[242:245], v[180:183], v[82:85]
	v_mfma_f32_16x16x32_bf16 v[26:29], v[242:245], v[188:191], v[26:29]
	s_waitcnt vmcnt(9)
	s_cmp_lt_u32 s6, 32
	s_cbranch_scc1 .Lmy_att_ok0
	s_waitcnt vmcnt(0)
.Lmy_att_ok0:
	ds_write_b128 v171, v[62:65] offset:14336
	ds_write_b128 v172, v[70:73] offset:37888
	s_and_saveexec_b64 s[4:5], s[36:37]
	s_cbranch_execz .Lmy_att_w0
	ds_write_b128 v169, v[2:5] offset:14336

; #define LAS __attribute__((address_space(3)))
; #define MFMA16(a, b, c) __builtin_amdgcn_mfma_f32_16x16x32_bf16((a), (b), (c), 0, 0, 0)
; __device__ __forceinline__ void attn_unit(LAS unsigned char* lds, const bf16_t* QB, const bf16_t* KB, const bf16_t* VT, const bf16_t* P, bf16_t* Z0, int b, int h, int qrow0, int nkeys) {
;     ...
;     for (int t2 = 0; t2 < ntile; t2 += 2) {
; #pragma unroll
;       for (int half = 0; half < 2; ++half) { const int tt = t2 + half; if (tt < ntile) {
;         const int cur = half;
;         const LAS unsigned char* kb = lds + cur * KBUF; const LAS unsigned char* vb = lds + VOFF + cur * VBUF;
;         f32x4 s[2][4];
; #pragma unroll
;         for (int kbk = 0; kbk < 4; ++kbk) { s[0][kbk] = (f32x4){0.f, 0.f, 0.f, 0.f}; s[1][kbk] = s[0][kbk];
; #pragma unroll
;             for (int ks = 0; ks < 3; ++ks) { const bf16x8 kf = *(const LAS bf16x8*)(kb + (kbk * 16 + fr) * KST + ks * 64 + fq * 16);
;                 s[0][kbk] = MFMA16(kf, qf[0][ks], s[0][kbk]); s[1][kbk] = MFMA16(kf, qf[1][ks], s[1][kbk]); } }
;         bf16x8 pf[2][2];
; #pragma unroll
;         for (int qb = 0; qb < 2; ++qb) {
;             float ps = 0.f;
; #pragma unroll
;             for (int kbk = 0; kbk < 4; ++kbk)
; #pragma unroll
;                 for (int q = 0; q < 4; ++q) { const float pv = __builtin_amdgcn_exp2f(s[qb][kbk][q]); s[qb][kbk][q] = pv; ps += pv; }
;             lsum[qb] += ps;
; #pragma unroll
;             for (int k2 = 0; k2 < 2; ++k2) { u32x4 w; w.x = cvt_pk_bf16(s[qb][2 * k2][0], s[qb][2 * k2][1]); w.y = cvt_pk_bf16(s[qb][2 * k2][2], s[qb][2 * k2][3]);
;                 w.z = cvt_pk_bf16(s[qb][2 * k2 + 1][0], s[qb][2 * k2 + 1][1]); w.w = cvt_pk_bf16(s[qb][2 * k2 + 1][2], s[qb][2 * k2 + 1][3]); pf[qb][k2] = asfrag(w); }
;         }
; #pragma unroll
;         for (int db = 0; db < 4; ++db)
; #pragma unroll
;             for (int k2 = 0; k2 < 2; ++k2) { const LAS unsigned char* vp = vb + (db * 16 + fr) * VST + (k2 * 32 + fq * 4) * 2;
;                 const u32x2 lo = *(const LAS u32x2*)vp, hi = *(const LAS u32x2*)(vp + 32);
;                 const bf16x8 vf = asfrag((u32x4){lo.x, lo.y, hi.x, hi.y});
;                 o[0][db] = MFMA16(vf, pf[0][k2], o[0][db]); o[1][db] = MFMA16(vf, pf[1][k2], o[1][db]); }
;         if (tt + 1 < ntile) ATT_STORE(half, cur ^ 1);
;         __syncthreads();
;         if (tt + 3 < ntile) ATT_LOAD(half, tt + 3);
.Lmy_att_nl0:
	v_mfma_f32_16x16x32_bf16 v[30:33], v[136:139], v[180:183], v[30:33]
	v_mfma_f32_16x16x32_bf16 v[14:17], v[136:139], v[188:191], v[14:17]
	s_waitcnt lgkmcnt(0)
	s_barrier
	ds_read_b128 v[132:135], v0 offset:14336
	ds_read_b128 v[136:139], v0 offset:14400
	ds_read_b128 v[140:143], v0 offset:14464
	ds_read_b128 v[156:159], v0 offset:17920
	ds_read_b128 v[160:163], v0 offset:17984
	ds_read_b128 v[164:167], v0 offset:18048
	ds_read_b128 v[238:241], v0 offset:21504
	ds_read_b128 v[242:245], v0 offset:21568
	ds_read_b128 v[246:249], v0 offset:21632
	s_waitcnt lgkmcnt(6)
	v_mfma_f32_16x16x32_bf16 v[100:103], v[132:135], v[34:37], 0
	v_mfma_f32_16x16x32_bf16 v[116:119], v[132:135], v[46:49], 0
	v_mfma_f32_16x16x32_bf16 v[100:103], v[136:139], v[38:41], v[100:103]
	v_mfma_f32_16x16x32_bf16 v[116:119], v[136:139], v[50:53], v[116:119]
	v_mfma_f32_16x16x32_bf16 v[100:103], v[140:143], v[42:45], v[100:103]
	v_mfma_f32_16x16x32_bf16 v[116:119], v[140:143], v[54:57], v[116:119]
	ds_read_b128 v[132:135], v0 offset:25088
	ds_read_b128 v[136:139], v0 offset:25152
	ds_read_b128 v[140:143], v0 offset:25216
	s_waitcnt lgkmcnt(6)
	v_mfma_f32_16x16x32_bf16 v[104:107], v[156:159], v[34:37], 0
	v_mfma_f32_16x16x32_bf16 v[120:123], v[156:159], v[46:49], 0
	v_mfma_f32_16x16x32_bf16 v[104:107], v[160:163], v[38:41], v[104:107]
	v_mfma_f32_16x16x32_bf16 v[120:123], v[160:163], v[50:53], v[120:123]
	v_mfma_f32_16x16x32_bf16 v[104:107], v[164:167], v[42:45], v[104:107]
	v_mfma_f32_16x16x32_bf16 v[120:123], v[164:167], v[54:57], v[120:123]
	ds_read_b64 v[156:157], v175 offset:37888
	ds_read_b64 v[158:159], v175 offset:37920
	ds_read_b64 v[160:161], v175 offset:40192
	ds_read_b64 v[162:163], v175 offset:40224
	ds_read_b64 v[164:165], v175 offset:42496
	ds_read_b64 v[166:167], v175 offset:42528
	s_waitcnt lgkmcnt(9)
	v_mfma_f32_16x16x32_bf16 v[108:111], v[238:241], v[34:37], 0
	v_exp_f32_e32 v100, v100
	v_exp_f32_e32 v101, v101
	v_exp_f32_e32 v102, v102
	v_exp_f32_e32 v103, v103
	v_mfma_f32_16x16x32_bf16 v[124:127], v[238:241], v[46:49], 0
	v_exp_f32_e32 v116, v116
	v_exp_f32_e32 v117, v117
	v_exp_f32_e32 v118, v118
	v_exp_f32_e32 v119, v119
	v_mfma_f32_16x16x32_bf16 v[108:111], v[242:245], v[38:41], v[108:111]
	v_add_f32_e32 v98, v98, v100
	v_add_f32_e32 v99, v99, v101
	v_cvt_pk_bf16_f32 v176, v100, v101
	v_mfma_f32_16x16x32_bf16 v[124:127], v[242:245], v[50:53], v[124:127]
	v_add_f32_e32 v98, v98, v102
	v_add_f32_e32 v99, v99, v103
	v_cvt_pk_bf16_f32 v177, v102, v103
	v_mfma_f32_16x16x32_bf16 v[108:111], v[246:249], v[42:45], v[108:111]
	v_add_f32_e32 v192, v192, v116
	v_add_f32_e32 v193, v193, v117
	v_cvt_pk_bf16_f32 v184, v116, v117
	v_mfma_f32_16x16x32_bf16 v[124:127], v[246:249], v[54:57], v[124:127]
	v_add_f32_e32 v192, v192, v118
	v_add_f32_e32 v193, v193, v119
	v_cvt_pk_bf16_f32 v185, v118, v119
	ds_read_b64 v[238:239], v175 offset:44800
	ds_read_b64 v[240:241], v175 offset:44832
	ds_read_b64 v[242:243], v175 offset:37952
	ds_read_b64 v[244:245], v175 offset:37984
	ds_read_b64 v[246:247], v175 offset:40256
	ds_read_b64 v[248:249], v175 offset:40288
	s_waitcnt lgkmcnt(12)
	v_mfma_f32_16x16x32_bf16 v[112:115], v[132:135], v[34:37], 0
	v_exp_f32_e32 v104, v104
	v_exp_f32_e32 v105, v105
	v_exp_f32_e32 v106, v106
	v_exp_f32_e32 v107, v107
	v_mfma_f32_16x16x32_bf16 v[128:131], v[132:135], v[46:49], 0
	v_exp_f32_e32 v120, v120
	v_exp_f32_e32 v121, v121
	v_exp_f32_e32 v122, v122
	v_exp_f32_e32 v123, v123
	v_mfma_f32_16x16x32_bf16 v[112:115], v[136:139], v[38:41], v[112:115]
	v_add_f32_e32 v98, v98, v104
	v_add_f32_e32 v99, v99, v105
	v_cvt_pk_bf16_f32 v178, v104, v105
	v_mfma_f32_16x16x32_bf16 v[128:131], v[136:139], v[50:53], v[128:131]
	v_add_f32_e32 v98, v98, v106
	v_add_f32_e32 v99, v99, v107
	v_cvt_pk_bf16_f32 v179, v106, v107
	v_mfma_f32_16x16x32_bf16 v[112:115], v[140:143], v[42:45], v[112:115]
	v_add_f32_e32 v192, v192, v120
	v_add_f32_e32 v193, v193, v121
	v_cvt_pk_bf16_f32 v186, v120, v121
	v_mfma_f32_16x16x32_bf16 v[128:131], v[140:143], v[54:57], v[128:131]
	v_add_f32_e32 v192, v192, v122
	v_add_f32_e32 v193, v193, v123
	v_cvt_pk_bf16_f32 v187, v122, v123
	s_waitcnt lgkmcnt(6)
	ds_read_b64 v[132:133], v175 offset:42560
	ds_read_b64 v[134:135], v175 offset:42592
	ds_read_b64 v[136:137], v175 offset:44864
	ds_read_b64 v[138:139], v175 offset:44896
	v_mfma_f32_16x16x32_bf16 v[82:85], v[156:159], v[176:179], v[82:85]
	v_exp_f32_e32 v108, v108
	v_exp_f32_e32 v109, v109
	v_exp_f32_e32 v110, v110
	v_exp_f32_e32 v111, v111
	v_exp_f32_e32 v124, v124
	v_mfma_f32_16x16x32_bf16 v[26:29], v[156:159], v[184:187], v[26:29]
	v_exp_f32_e32 v125, v125
	v_exp_f32_e32 v126, v126
	v_exp_f32_e32 v127, v127
	v_add_f32_e32 v98, v98, v108
	v_add_f32_e32 v99, v99, v109
	v_mfma_f32_16x16x32_bf16 v[74:77], v[160:163], v[176:179], v[74:77]
	v_cvt_pk_bf16_f32 v180, v108, v109
	v_add_f32_e32 v98, v98, v110
	v_add_f32_e32 v99, v99, v111
	v_cvt_pk_bf16_f32 v181, v110, v111
	v_add_f32_e32 v192, v192, v124
	v_mfma_f32_16x16x32_bf16 v[22:25], v[160:163], v[184:187], v[22:25]
	v_add_f32_e32 v193, v193, v125
	v_cvt_pk_bf16_f32 v188, v124, v125
	v_add_f32_e32 v192, v192, v126
	v_add_f32_e32 v193, v193, v127
	v_cvt_pk_bf16_f32 v189, v126, v127
	v_mfma_f32_16x16x32_bf16 v[58:61], v[164:167], v[176:179], v[58:61]
	v_exp_f32_e32 v112, v112
	v_exp_f32_e32 v113, v113
	v_exp_f32_e32 v114, v114
	v_exp_f32_e32 v115, v115
	v_exp_f32_e32 v128, v128
	v_mfma_f32_16x16x32_bf16 v[18:21], v[164:167], v[184:187], v[18:21]
	v_exp_f32_e32 v129, v129
	v_exp_f32_e32 v130, v130
	v_exp_f32_e32 v131, v131
	v_add_f32_e32 v98, v98, v112
	v_add_f32_e32 v99, v99, v113
	s_waitcnt lgkmcnt(8)
	v_mfma_f32_16x16x32_bf16 v[30:33], v[238:241], v[176:179], v[30:33]
	v_cvt_pk_bf16_f32 v182, v112, v113
	v_add_f32_e32 v98, v98, v114
	v_add_f32_e32 v99, v99, v115
	v_cvt_pk_bf16_f32 v183, v114, v115
	v_add_f32_e32 v192, v192, v128
	v_mfma_f32_16x16x32_bf16 v[14:17], v[238:241], v[184:187], v[14:17]
	v_add_f32_e32 v193, v193, v129
	v_cvt_pk_bf16_f32 v190, v128, v129
	v_add_f32_e32 v192, v192, v130
	v_add_f32_e32 v193, v193, v131
	v_cvt_pk_bf16_f32 v191, v130, v131
	s_waitcnt lgkmcnt(0)
	v_mfma_f32_16x16x32_bf16 v[82:85], v[242:245], v[180:183], v[82:85]
	v_mfma_f32_16x16x32_bf16 v[26:29], v[242:245], v[188:191], v[26:29]
	s_waitcnt vmcnt(9)
	s_cmp_lt_u32 s6, 32
	s_cbranch_scc1 .Lmy_att_ok1
	s_waitcnt vmcnt(0)
.Lmy_att_ok1:
	ds_write_b128 v171, v[66:69]
	ds_write_b128 v172, v[78:81] offset:28672
	s_and_saveexec_b64 s[4:5], s[36:37]
	s_cbranch_execz .Lmy_att_w1
	ds_write_b128 v169, v[6:9]

; #define LAS __attribute__((address_space(3)))
; #define MFMA16(a, b, c) __builtin_amdgcn_mfma_f32_16x16x32_bf16((a), (b), (c), 0, 0, 0)
; __device__ __forceinline__ void attn_unit(LAS unsigned char* lds, const bf16_t* QB, const bf16_t* KB, const bf16_t* VT, const bf16_t* P, bf16_t* Z0, int b, int h, int qrow0, int nkeys) {
;     ...
;     for (int t2 = 0; t2 < ntile; t2 += 2) {
; #pragma unroll
;       for (int half = 0; half < 2; ++half) { const int tt = t2 + half; if (tt < ntile) {
;         const int cur = half;
;         const LAS unsigned char* kb = lds + cur * KBUF; const LAS unsigned char* vb = lds + VOFF + cur * VBUF;
;         f32x4 s[2][4];
; #pragma unroll
;         for (int kbk = 0; kbk < 4; ++kbk) { s[0][kbk] = (f32x4){0.f, 0.f, 0.f, 0.f}; s[1][kbk] = s[0][kbk];
; #pragma unroll
;             for (int ks = 0; ks < 3; ++ks) { const bf16x8 kf = *(const LAS bf16x8*)(kb + (kbk * 16 + fr) * KST + ks * 64 + fq * 16);
;                 s[0][kbk] = MFMA16(kf, qf[0][ks], s[0][kbk]); s[1][kbk] = MFMA16(kf, qf[1][ks], s[1][kbk]); } }
;         bf16x8 pf[2][2];
; #pragma unroll
;         for (int qb = 0; qb < 2; ++qb) {
;             float ps = 0.f;
; #pragma unroll
;             for (int kbk = 0; kbk < 4; ++kbk)
; #pragma unroll
;                 for (int q = 0; q < 4; ++q) { const float pv = __builtin_amdgcn_exp2f(s[qb][kbk][q]); s[qb][kbk][q] = pv; ps += pv; }
;             lsum[qb] += ps;
; #pragma unroll
;             for (int k2 = 0; k2 < 2; ++k2) { u32x4 w; w.x = cvt_pk_bf16(s[qb][2 * k2][0], s[qb][2 * k2][1]); w.y = cvt_pk_bf16(s[qb][2 * k2][2], s[qb][2 * k2][3]);
;                 w.z = cvt_pk_bf16(s[qb][2 * k2 + 1][0], s[qb][2 * k2 + 1][1]); w.w = cvt_pk_bf16(s[qb][2 * k2 + 1][2], s[qb][2 * k2 + 1][3]); pf[qb][k2] = asfrag(w); }
;         }
; #pragma unroll
;         for (int db = 0; db < 4; ++db)
; #pragma unroll
;             for (int k2 = 0; k2 < 2; ++k2) { const LAS unsigned char* vp = vb + (db * 16 + fr) * VST + (k2 * 32 + fq * 4) * 2;
;                 const u32x2 lo = *(const LAS u32x2*)vp, hi = *(const LAS u32x2*)(vp + 32);
;                 const bf16x8 vf = asfrag((u32x4){lo.x, lo.y, hi.x, hi.y});
;                 o[0][db] = MFMA16(vf, pf[0][k2], o[0][db]); o[1][db] = MFMA16(vf, pf[1][k2], o[1][db]); }
;         if (tt + 1 < ntile) ATT_STORE(half, cur ^ 1);
;         __syncthreads();
;         if (tt + 3 < ntile) ATT_LOAD(half, tt + 3);
.Lmy_att_nl1:
	v_mfma_f32_16x16x32_bf16 v[30:33], v[136:139], v[180:183], v[30:33]
	v_mfma_f32_16x16x32_bf16 v[14:17], v[136:139], v[188:191], v[14:17]
	s_waitcnt lgkmcnt(0)
	s_barrier
	ds_read_b128 v[132:135], v0 offset:0
	ds_read_b128 v[136:139], v0 offset:64
	ds_read_b128 v[140:143], v0 offset:128
	ds_read_b128 v[156:159], v0 offset:3584
	ds_read_b128 v[160:163], v0 offset:3648
	ds_read_b128 v[164:167], v0 offset:3712
	ds_read_b128 v[238:241], v0 offset:7168
	ds_read_b128 v[242:245], v0 offset:7232
	ds_read_b128 v[246:249], v0 offset:7296
	s_waitcnt lgkmcnt(6)
	v_mfma_f32_16x16x32_bf16 v[100:103], v[132:135], v[34:37], 0
	v_mfma_f32_16x16x32_bf16 v[116:119], v[132:135], v[46:49], 0
	v_mfma_f32_16x16x32_bf16 v[100:103], v[136:139], v[38:41], v[100:103]
	v_mfma_f32_16x16x32_bf16 v[116:119], v[136:139], v[50:53], v[116:119]
	v_mfma_f32_16x16x32_bf16 v[100:103], v[140:143], v[42:45], v[100:103]
	v_mfma_f32_16x16x32_bf16 v[116:119], v[140:143], v[54:57], v[116:119]
	ds_read_b128 v[132:135], v0 offset:10752
	ds_read_b128 v[136:139], v0 offset:10816
	ds_read_b128 v[140:143], v0 offset:10880
	s_waitcnt lgkmcnt(6)
	v_mfma_f32_16x16x32_bf16 v[104:107], v[156:159], v[34:37], 0
	v_mfma_f32_16x16x32_bf16 v[120:123], v[156:159], v[46:49], 0
	v_mfma_f32_16x16x32_bf16 v[104:107], v[160:163], v[38:41], v[104:107]
	v_mfma_f32_16x16x32_bf16 v[120:123], v[160:163], v[50:53], v[120:123]
	v_mfma_f32_16x16x32_bf16 v[104:107], v[164:167], v[42:45], v[104:107]
	v_mfma_f32_16x16x32_bf16 v[120:123], v[164:167], v[54:57], v[120:123]
	ds_read_b64 v[156:157], v175 offset:28672
	ds_read_b64 v[158:159], v175 offset:28704
	ds_read_b64 v[160:161], v175 offset:30976
	ds_read_b64 v[162:163], v175 offset:31008
	ds_read_b64 v[164:165], v175 offset:33280
	ds_read_b64 v[166:167], v175 offset:33312
	s_waitcnt lgkmcnt(9)
	v_mfma_f32_16x16x32_bf16 v[108:111], v[238:241], v[34:37], 0
	v_exp_f32_e32 v100, v100
	v_exp_f32_e32 v101, v101
	v_exp_f32_e32 v102, v102
	v_exp_f32_e32 v103, v103
	v_mfma_f32_16x16x32_bf16 v[124:127], v[238:241], v[46:49], 0
	v_exp_f32_e32 v116, v116
	v_exp_f32_e32 v117, v117
	v_exp_f32_e32 v118, v118
	v_exp_f32_e32 v119, v119
	v_mfma_f32_16x16x32_bf16 v[108:111], v[242:245], v[38:41], v[108:111]
	v_add_f32_e32 v98, v98, v100
	v_add_f32_e32 v99, v99, v101
	v_cvt_pk_bf16_f32 v176, v100, v101
	v_mfma_f32_16x16x32_bf16 v[124:127], v[242:245], v[50:53], v[124:127]
	v_add_f32_e32 v98, v98, v102
	v_add_f32_e32 v99, v99, v103
	v_cvt_pk_bf16_f32 v177, v102, v103
	v_mfma_f32_16x16x32_bf16 v[108:111], v[246:249], v[42:45], v[108:111]
	v_add_f32_e32 v192, v192, v116
	v_add_f32_e32 v193, v193, v117
	v_cvt_pk_bf16_f32 v184, v116, v117
	v_mfma_f32_16x16x32_bf16 v[124:127], v[246:249], v[54:57], v[124:127]
	v_add_f32_e32 v192, v192, v118
	v_add_f32_e32 v193, v193, v119
	v_cvt_pk_bf16_f32 v185, v118, v119
	ds_read_b64 v[238:239], v175 offset:35584
	ds_read_b64 v[240:241], v175 offset:35616
	ds_read_b64 v[242:243], v175 offset:28736
	ds_read_b64 v[244:245], v175 offset:28768
	ds_read_b64 v[246:247], v175 offset:31040
	ds_read_b64 v[248:249], v175 offset:31072
	s_waitcnt lgkmcnt(12)
	v_mfma_f32_16x16x32_bf16 v[112:115], v[132:135], v[34:37], 0
	v_exp_f32_e32 v104, v104
	v_exp_f32_e32 v105, v105
	v_exp_f32_e32 v106, v106
	v_exp_f32_e32 v107, v107
	v_mfma_f32_16x16x32_bf16 v[128:131], v[132:135], v[46:49], 0
	v_exp_f32_e32 v120, v120
	v_exp_f32_e32 v121, v121
	v_exp_f32_e32 v122, v122
	v_exp_f32_e32 v123, v123
	v_mfma_f32_16x16x32_bf16 v[112:115], v[136:139], v[38:41], v[112:115]
	v_add_f32_e32 v98, v98, v104
	v_add_f32_e32 v99, v99, v105
	v_cvt_pk_bf16_f32 v178, v104, v105
	v_mfma_f32_16x16x32_bf16 v[128:131], v[136:139], v[50:53], v[128:131]
	v_add_f32_e32 v98, v98, v106
	v_add_f32_e32 v99, v99, v107
	v_cvt_pk_bf16_f32 v179, v106, v107
	v_mfma_f32_16x16x32_bf16 v[112:115], v[140:143], v[42:45], v[112:115]
	v_add_f32_e32 v192, v192, v120
	v_add_f32_e32 v193, v193, v121
	v_cvt_pk_bf16_f32 v186, v120, v121
	v_mfma_f32_16x16x32_bf16 v[128:131], v[140:143], v[54:57], v[128:131]
	v_add_f32_e32 v192, v192, v122
	v_add_f32_e32 v193, v193, v123
	v_cvt_pk_bf16_f32 v187, v122, v123
	s_waitcnt lgkmcnt(6)
	ds_read_b64 v[132:133], v175 offset:33344
	ds_read_b64 v[134:135], v175 offset:33376
	ds_read_b64 v[136:137], v175 offset:35648
	ds_read_b64 v[138:139], v175 offset:35680
	v_mfma_f32_16x16x32_bf16 v[82:85], v[156:159], v[176:179], v[82:85]
	v_exp_f32_e32 v108, v108
	v_exp_f32_e32 v109, v109
	v_exp_f32_e32 v110, v110
	v_exp_f32_e32 v111, v111
	v_exp_f32_e32 v124, v124
	v_mfma_f32_16x16x32_bf16 v[26:29], v[156:159], v[184:187], v[26:29]
	v_exp_f32_e32 v125, v125
	v_exp_f32_e32 v126, v126
	v_exp_f32_e32 v127, v127
	v_add_f32_e32 v98, v98, v108
	v_add_f32_e32 v99, v99, v109
	v_mfma_f32_16x16x32_bf16 v[74:77], v[160:163], v[176:179], v[74:77]
	v_cvt_pk_bf16_f32 v180, v108, v109
	v_add_f32_e32 v98, v98, v110
	v_add_f32_e32 v99, v99, v111
	v_cvt_pk_bf16_f32 v181, v110, v111
	v_add_f32_e32 v192, v192, v124
	v_mfma_f32_16x16x32_bf16 v[22:25], v[160:163], v[184:187], v[22:25]
	v_add_f32_e32 v193, v193, v125
	v_cvt_pk_bf16_f32 v188, v124, v125
	v_add_f32_e32 v192, v192, v126
	v_add_f32_e32 v193, v193, v127
	v_cvt_pk_bf16_f32 v189, v126, v127
	v_mfma_f32_16x16x32_bf16 v[58:61], v[164:167], v[176:179], v[58:61]
	v_exp_f32_e32 v112, v112
	v_exp_f32_e32 v113, v113
	v_exp_f32_e32 v114, v114
	v_exp_f32_e32 v115, v115
	v_exp_f32_e32 v128, v128
	v_mfma_f32_16x16x32_bf16 v[18:21], v[164:167], v[184:187], v[18:21]
	v_exp_f32_e32 v129, v129
	v_exp_f32_e32 v130, v130
	v_exp_f32_e32 v131, v131
	v_add_f32_e32 v98, v98, v112
	v_add_f32_e32 v99, v99, v113
	s_waitcnt lgkmcnt(8)
	v_mfma_f32_16x16x32_bf16 v[30:33], v[238:241], v[176:179], v[30:33]
	v_cvt_pk_bf16_f32 v182, v112, v113
	v_add_f32_e32 v98, v98, v114
	v_add_f32_e32 v99, v99, v115
	v_cvt_pk_bf16_f32 v183, v114, v115
	v_add_f32_e32 v192, v192, v128
	v_mfma_f32_16x16x32_bf16 v[14:17], v[238:241], v[184:187], v[14:17]
	v_add_f32_e32 v193, v193, v129
	v_cvt_pk_bf16_f32 v190, v128, v129
	v_add_f32_e32 v192, v192, v130
	v_add_f32_e32 v193, v193, v131
	v_cvt_pk_bf16_f32 v191, v130, v131
	s_waitcnt lgkmcnt(0)
	v_mfma_f32_16x16x32_bf16 v[82:85], v[242:245], v[180:183], v[82:85]
	v_mfma_f32_16x16x32_bf16 v[26:29], v[242:245], v[188:191], v[26:29]
	s_waitcnt vmcnt(9)
	s_cmp_lt_u32 s6, 32
	s_cbranch_scc1 .Lmy_att_ok2
	s_waitcnt vmcnt(0)
.Lmy_att_ok2:
	ds_write_b128 v171, v[214:217] offset:14336
	ds_write_b128 v172, v[222:225] offset:37888
	s_and_saveexec_b64 s[4:5], s[36:37]
	s_cbranch_execz .Lmy_att_w2
	ds_write_b128 v169, v[218:221] offset:14336

; #define LAS __attribute__((address_space(3)))
; #define MFMA16(a, b, c) __builtin_amdgcn_mfma_f32_16x16x32_bf16((a), (b), (c), 0, 0, 0)
; __device__ __forceinline__ void attn_unit(LAS unsigned char* lds, const bf16_t* QB, const bf16_t* KB, const bf16_t* VT, const bf16_t* P, bf16_t* Z0, int b, int h, int qrow0, int nkeys) {
;     ...
;     for (int t2 = 0; t2 < ntile; t2 += 2) {
; #pragma unroll
;       for (int half = 0; half < 2; ++half) { const int tt = t2 + half; if (tt < ntile) {
;         const int cur = half;
;         const LAS unsigned char* kb = lds + cur * KBUF; const LAS unsigned char* vb = lds + VOFF + cur * VBUF;
;         f32x4 s[2][4];
; #pragma unroll
;         for (int kbk = 0; kbk < 4; ++kbk) { s[0][kbk] = (f32x4){0.f, 0.f, 0.f, 0.f}; s[1][kbk] = s[0][kbk];
; #pragma unroll
;             for (int ks = 0; ks < 3; ++ks) { const bf16x8 kf = *(const LAS bf16x8*)(kb + (kbk * 16 + fr) * KST + ks * 64 + fq * 16);
;                 s[0][kbk] = MFMA16(kf, qf[0][ks], s[0][kbk]); s[1][kbk] = MFMA16(kf, qf[1][ks], s[1][kbk]); } }
;         bf16x8 pf[2][2];
; #pragma unroll
;         for (int qb = 0; qb < 2; ++qb) {
;             float ps = 0.f;
; #pragma unroll
;             for (int kbk = 0; kbk < 4; ++kbk)
; #pragma unroll
;                 for (int q = 0; q < 4; ++q) { const float pv = __builtin_amdgcn_exp2f(s[qb][kbk][q]); s[qb][kbk][q] = pv; ps += pv; }
;             lsum[qb] += ps;
; #pragma unroll
;             for (int k2 = 0; k2 < 2; ++k2) { u32x4 w; w.x = cvt_pk_bf16(s[qb][2 * k2][0], s[qb][2 * k2][1]); w.y = cvt_pk_bf16(s[qb][2 * k2][2], s[qb][2 * k2][3]);
;                 w.z = cvt_pk_bf16(s[qb][2 * k2 + 1][0], s[qb][2 * k2 + 1][1]); w.w = cvt_pk_bf16(s[qb][2 * k2 + 1][2], s[qb][2 * k2 + 1][3]); pf[qb][k2] = asfrag(w); }
;         }
; #pragma unroll
;         for (int db = 0; db < 4; ++db)
; #pragma unroll
;             for (int k2 = 0; k2 < 2; ++k2) { const LAS unsigned char* vp = vb + (db * 16 + fr) * VST + (k2 * 32 + fq * 4) * 2;
;                 const u32x2 lo = *(const LAS u32x2*)vp, hi = *(const LAS u32x2*)(vp + 32);
;                 const bf16x8 vf = asfrag((u32x4){lo.x, lo.y, hi.x, hi.y});
;                 o[0][db] = MFMA16(vf, pf[0][k2], o[0][db]); o[1][db] = MFMA16(vf, pf[1][k2], o[1][db]); }
;         if (tt + 1 < ntile) ATT_STORE(half, cur ^ 1);
;         __syncthreads();
;         if (tt + 3 < ntile) ATT_LOAD(half, tt + 3);
.Lmy_att_nl2:
	v_mfma_f32_16x16x32_bf16 v[30:33], v[136:139], v[180:183], v[30:33]
	v_mfma_f32_16x16x32_bf16 v[14:17], v[136:139], v[188:191], v[14:17]
	s_waitcnt lgkmcnt(0)
	s_barrier
	ds_read_b128 v[132:135], v0 offset:14336
	ds_read_b128 v[136:139], v0 offset:14400
	ds_read_b128 v[140:143], v0 offset:14464
	ds_read_b128 v[156:159], v0 offset:17920
	ds_read_b128 v[160:163], v0 offset:17984
	ds_read_b128 v[164:167], v0 offset:18048
	ds_read_b128 v[238:241], v0 offset:21504
	ds_read_b128 v[242:245], v0 offset:21568
	ds_read_b128 v[246:249], v0 offset:21632
	s_waitcnt lgkmcnt(6)
	v_mfma_f32_16x16x32_bf16 v[100:103], v[132:135], v[34:37], 0
	v_mfma_f32_16x16x32_bf16 v[116:119], v[132:135], v[46:49], 0
	v_mfma_f32_16x16x32_bf16 v[100:103], v[136:139], v[38:41], v[100:103]
	v_mfma_f32_16x16x32_bf16 v[116:119], v[136:139], v[50:53], v[116:119]
	v_mfma_f32_16x16x32_bf16 v[100:103], v[140:143], v[42:45], v[100:103]
	v_mfma_f32_16x16x32_bf16 v[116:119], v[140:143], v[54:57], v[116:119]
	ds_read_b128 v[132:135], v0 offset:25088
	ds_read_b128 v[136:139], v0 offset:25152
	ds_read_b128 v[140:143], v0 offset:25216
	s_waitcnt lgkmcnt(6)
	v_mfma_f32_16x16x32_bf16 v[104:107], v[156:159], v[34:37], 0
	v_mfma_f32_16x16x32_bf16 v[120:123], v[156:159], v[46:49], 0
	v_mfma_f32_16x16x32_bf16 v[104:107], v[160:163], v[38:41], v[104:107]
	v_mfma_f32_16x16x32_bf16 v[120:123], v[160:163], v[50:53], v[120:123]
	v_mfma_f32_16x16x32_bf16 v[104:107], v[164:167], v[42:45], v[104:107]
	v_mfma_f32_16x16x32_bf16 v[120:123], v[164:167], v[54:57], v[120:123]
	ds_read_b64 v[156:157], v175 offset:37888
	ds_read_b64 v[158:159], v175 offset:37920
	ds_read_b64 v[160:161], v175 offset:40192
	ds_read_b64 v[162:163], v175 offset:40224
	ds_read_b64 v[164:165], v175 offset:42496
	ds_read_b64 v[166:167], v175 offset:42528
	s_waitcnt lgkmcnt(9)
	v_mfma_f32_16x16x32_bf16 v[108:111], v[238:241], v[34:37], 0
	v_exp_f32_e32 v100, v100
	v_exp_f32_e32 v101, v101
	v_exp_f32_e32 v102, v102
	v_exp_f32_e32 v103, v103
	v_mfma_f32_16x16x32_bf16 v[124:127], v[238:241], v[46:49], 0
	v_exp_f32_e32 v116, v116
	v_exp_f32_e32 v117, v117
	v_exp_f32_e32 v118, v118
	v_exp_f32_e32 v119, v119
	v_mfma_f32_16x16x32_bf16 v[108:111], v[242:245], v[38:41], v[108:111]
	v_add_f32_e32 v98, v98, v100
	v_add_f32_e32 v99, v99, v101
	v_cvt_pk_bf16_f32 v176, v100, v101
	v_mfma_f32_16x16x32_bf16 v[124:127], v[242:245], v[50:53], v[124:127]
	v_add_f32_e32 v98, v98, v102
	v_add_f32_e32 v99, v99, v103
	v_cvt_pk_bf16_f32 v177, v102, v103
	v_mfma_f32_16x16x32_bf16 v[108:111], v[246:249], v[42:45], v[108:111]
	v_add_f32_e32 v192, v192, v116
	v_add_f32_e32 v193, v193, v117
	v_cvt_pk_bf16_f32 v184, v116, v117
	v_mfma_f32_16x16x32_bf16 v[124:127], v[246:249], v[54:57], v[124:127]
	v_add_f32_e32 v192, v192, v118
	v_add_f32_e32 v193, v193, v119
	v_cvt_pk_bf16_f32 v185, v118, v119
	ds_read_b64 v[238:239], v175 offset:44800
	ds_read_b64 v[240:241], v175 offset:44832
	ds_read_b64 v[242:243], v175 offset:37952
	ds_read_b64 v[244:245], v175 offset:37984
	ds_read_b64 v[246:247], v175 offset:40256
	ds_read_b64 v[248:249], v175 offset:40288
	s_waitcnt lgkmcnt(12)
	v_mfma_f32_16x16x32_bf16 v[112:115], v[132:135], v[34:37], 0
	v_exp_f32_e32 v104, v104
	v_exp_f32_e32 v105, v105
	v_exp_f32_e32 v106, v106
	v_exp_f32_e32 v107, v107
	v_mfma_f32_16x16x32_bf16 v[128:131], v[132:135], v[46:49], 0
	v_exp_f32_e32 v120, v120
	v_exp_f32_e32 v121, v121
	v_exp_f32_e32 v122, v122
	v_exp_f32_e32 v123, v123
	v_mfma_f32_16x16x32_bf16 v[112:115], v[136:139], v[38:41], v[112:115]
	v_add_f32_e32 v98, v98, v104
	v_add_f32_e32 v99, v99, v105
	v_cvt_pk_bf16_f32 v178, v104, v105
	v_mfma_f32_16x16x32_bf16 v[128:131], v[136:139], v[50:53], v[128:131]
	v_add_f32_e32 v98, v98, v106
	v_add_f32_e32 v99, v99, v107
	v_cvt_pk_bf16_f32 v179, v106, v107
	v_mfma_f32_16x16x32_bf16 v[112:115], v[140:143], v[42:45], v[112:115]
	v_add_f32_e32 v192, v192, v120
	v_add_f32_e32 v193, v193, v121
	v_cvt_pk_bf16_f32 v186, v120, v121
	v_mfma_f32_16x16x32_bf16 v[128:131], v[140:143], v[54:57], v[128:131]
	v_add_f32_e32 v192, v192, v122
	v_add_f32_e32 v193, v193, v123
	v_cvt_pk_bf16_f32 v187, v122, v123
	s_waitcnt lgkmcnt(6)
	ds_read_b64 v[132:133], v175 offset:42560
	ds_read_b64 v[134:135], v175 offset:42592
	ds_read_b64 v[136:137], v175 offset:44864
	ds_read_b64 v[138:139], v175 offset:44896
	v_mfma_f32_16x16x32_bf16 v[82:85], v[156:159], v[176:179], v[82:85]
	v_exp_f32_e32 v108, v108
	v_exp_f32_e32 v109, v109
	v_exp_f32_e32 v110, v110
	v_exp_f32_e32 v111, v111
	v_exp_f32_e32 v124, v124
	v_mfma_f32_16x16x32_bf16 v[26:29], v[156:159], v[184:187], v[26:29]
	v_exp_f32_e32 v125, v125
	v_exp_f32_e32 v126, v126
	v_exp_f32_e32 v127, v127
	v_add_f32_e32 v98, v98, v108
	v_add_f32_e32 v99, v99, v109
	v_mfma_f32_16x16x32_bf16 v[74:77], v[160:163], v[176:179], v[74:77]
	v_cvt_pk_bf16_f32 v180, v108, v109
	v_add_f32_e32 v98, v98, v110
	v_add_f32_e32 v99, v99, v111
	v_cvt_pk_bf16_f32 v181, v110, v111
	v_add_f32_e32 v192, v192, v124
	v_mfma_f32_16x16x32_bf16 v[22:25], v[160:163], v[184:187], v[22:25]
	v_add_f32_e32 v193, v193, v125
	v_cvt_pk_bf16_f32 v188, v124, v125
	v_add_f32_e32 v192, v192, v126
	v_add_f32_e32 v193, v193, v127
	v_cvt_pk_bf16_f32 v189, v126, v127
	v_mfma_f32_16x16x32_bf16 v[58:61], v[164:167], v[176:179], v[58:61]
	v_exp_f32_e32 v112, v112
	v_exp_f32_e32 v113, v113
	v_exp_f32_e32 v114, v114
	v_exp_f32_e32 v115, v115
	v_exp_f32_e32 v128, v128
	v_mfma_f32_16x16x32_bf16 v[18:21], v[164:167], v[184:187], v[18:21]
	v_exp_f32_e32 v129, v129
	v_exp_f32_e32 v130, v130
	v_exp_f32_e32 v131, v131
	v_add_f32_e32 v98, v98, v112
	v_add_f32_e32 v99, v99, v113
	s_waitcnt lgkmcnt(8)
	v_mfma_f32_16x16x32_bf16 v[30:33], v[238:241], v[176:179], v[30:33]
	v_cvt_pk_bf16_f32 v182, v112, v113
	v_add_f32_e32 v98, v98, v114
	v_add_f32_e32 v99, v99, v115
	v_cvt_pk_bf16_f32 v183, v114, v115
	v_add_f32_e32 v192, v192, v128
	v_mfma_f32_16x16x32_bf16 v[14:17], v[238:241], v[184:187], v[14:17]
	v_add_f32_e32 v193, v193, v129
	v_cvt_pk_bf16_f32 v190, v128, v129
	v_add_f32_e32 v192, v192, v130
	v_add_f32_e32 v193, v193, v131
	v_cvt_pk_bf16_f32 v191, v130, v131
	s_waitcnt lgkmcnt(0)
	v_mfma_f32_16x16x32_bf16 v[82:85], v[242:245], v[180:183], v[82:85]
	v_mfma_f32_16x16x32_bf16 v[26:29], v[242:245], v[188:191], v[26:29]
	s_cmp_gt_u32 s6, 28
	s_cbranch_scc1 .Lmy_att_ns3
	s_waitcnt vmcnt(9)
	ds_write_b128 v171, v[226:229]
	ds_write_b128 v172, v[234:237] offset:28672
	s_and_saveexec_b64 s[4:5], s[36:37]
	s_cbranch_execz .Lmy_att_w3
	ds_write_b128 v169, v[230:233]

; __device__ __forceinline__ unsigned xb_add(unsigned* p, unsigned v) { return __hip_atomic_fetch_add(p, v, __ATOMIC_RELAXED, __HIP_MEMORY_SCOPE_AGENT); }
; #define ATT_LOAD(S_, tt) do { const bf16_t* kt_ = kg + (size_t)(tt) * 64 * 96; rk0[S_] = ld8(kt_ + kp0 * 8); if (kp1 < 768) rk1[S_] = ld8(kt_ + kp1 * 8); rv[S_] = ld8(vg + (size_t)vd * NKEY + (tt) * 64 + vpart * 8); } while (0)
; #define ATT_STORE(S_, bufi) do { LAS unsigned char* kb_ = lds + (bufi) * KBUF; *(LAS u32x4*)(kb_ + (kp0 / 12) * KST + (kp0 % 12) * 16) = rk0[S_]; if (kp1 < 768) *(LAS u32x4*)(kb_ + (kp1 / 12) * KST + (kp1 % 12) * 16) = rk1[S_]; \
;         *(LAS u32x4*)(lds + VOFF + (bufi) * VBUF + vd * VST + vpart * 16) = rv[S_]; } while (0)
; __device__ __forceinline__ void xcd_barrier(const XcdBarrier& b) {
;     asm volatile("s_waitcnt vmcnt(0)" ::: "memory");
;     __syncthreads();
;     if (threadIdx.x == 0) {
;         unsigned* bar = b.bar;
;         __builtin_amdgcn_s_waitcnt(0);
;         unsigned nloc = b.st[0], nx = b.st[1];
;         if (nloc == 0u) { xcd_barrier_complete(bar, b.x, nloc, nx); b.st[0] = nloc; b.st[1] = nx; }
;         const unsigned old = xb_add(&bar[XB_XSUB(b.x)], 1u);
; __device__ __forceinline__ void attn_unit(LAS unsigned char* lds, const bf16_t* QB, const bf16_t* KB, const bf16_t* VT, const bf16_t* P, bf16_t* Z0, int b, int h, int qrow0, int nkeys) {
;     ...
;         if (tt + 1 < ntile) ATT_STORE(half, cur ^ 1);
;         __syncthreads();
;         if (tt + 3 < ntile) ATT_LOAD(half, tt + 3);
;       } }
;     }
;     ...
; #pragma unroll
;     for (int qb = 0; qb < 2; ++qb) {
;         float lt = lsum[qb]; lt += __shfl_xor(lt, 16); lt += __shfl_xor(lt, 32);
.Lmy_att_nl3:
	v_mfma_f32_16x16x32_bf16 v[30:33], v[136:139], v[180:183], v[30:33]
	v_mfma_f32_16x16x32_bf16 v[14:17], v[136:139], v[188:191], v[14:17]
	s_waitcnt lgkmcnt(0)
	s_barrier
	s_add_i32 s6, s6, 4
	s_cmp_lt_u32 s6, 36
	s_cbranch_scc1 .Lmy_att_loop
	s_setprio 0
	s_nop 1
	v_add_f32_e32 v88, v98, v99
	v_add_f32_e32 v89, v192, v193
	s_branch .LBB0_1008
	s_branch .Lmy_pad_LBB01065
	s_nop 0
	s_nop 0
	s_nop 0
	s_nop 0
	s_nop 0
	s_nop 0
	s_nop 0
	s_nop 0
	s_nop 0
	s_nop 0
	s_nop 0
	s_nop 0
	s_nop 0
	s_nop 0
.Lmy_pad_LBB01065:
.LBB0_1065:
	s_waitcnt vmcnt(0)
	s_waitcnt lgkmcnt(0)
	s_barrier
	s_and_saveexec_b64 s[4:5], s[96:97]
	v_readlane_b32 s14, v253, 53
	v_readlane_b32 s18, v252, 10
	v_readlane_b32 s26, v252, 12
	s_xor_b64 s[4:5], exec, s[4:5]
	v_readlane_b32 s15, v253, 54
	v_readlane_b32 s19, v252, 11
	v_readlane_b32 s27, v252, 13
	s_cbranch_execz .LBB0_1114
	v_readlane_b32 s1, v253, 44
	s_waitcnt vmcnt(0) expcnt(0) lgkmcnt(0)
	s_nop 0
	v_mov_b32_e32 v0, s1
	ds_read_b32 v3, v0
	v_readlane_b32 s1, v253, 45
	s_waitcnt lgkmcnt(0)
	v_cmp_ne_u32_e32 vcc, 0, v3
	v_mov_b32_e32 v0, s1
	ds_read_b32 v2, v0
	s_cbranch_vccnz .LBB0_1081
	s_mov_b32 s1, 1
	s_branch .LBB0_1069

; __global__ void __launch_bounds__(512, 2) fwd_kernel(KArgs a) {
;     ...
;             if (!(l == 1 && hf == 1)) {
;             { const int la_ = (hf == 1 ? l + 1 : l), ha_ = (hf == 1 ? 0 : 1); { const int l = la_, hf = ha_; (void)l; (void)hf;
;             for (int rep_ = 0; rep_ < REP_A; ++rep_) {
;             { IDS;
;             for (int row = gw; row < MH; row += NGW) {
;                 const bool isc = row >= ML; const int rr = isc ? row - ML : row;
;                 const float* xr = (isc ? xcin : xin) + (size_t)rr * 1024;
;                 const float* md = modl + (size_t)(isc ? 16 : hf * HB + (row >> 11)) * 3072;
;                 const float* ng = a.in[6] + l * 1024;
;                 f32x4 v[4]; float ss = 0.f;
.LBB0_1586:
	v_readlane_b32 s4, v253, 49
	v_readlane_b32 s22, v250, 25
	v_readlane_b32 s5, v253, 50
	v_readlane_b32 s23, v250, 26
	s_and_b64 s[4:5], s[4:5], s[22:23]
	s_and_b64 vcc, exec, s[4:5]
	s_cbranch_vccnz .LBB0_1593
	s_mov_b64 s[4:5], s[72:73]
	v_mov_b32 v2, v194
	s_nop 0
	v_readfirstlane_b32 s1, v2
	s_ashr_i32 s20, s1, 6
	s_add_i32 s1, s20, s69
	s_mov_b32 s54, 0
	s_mov_b32 s55, s60
	s_cmp_lg_u32 s18, 0
	s_cbranch_scc1 .Lmy_ap_norm
	s_cmp_lg_u32 s60, 0x800
	s_cbranch_scc1 .Lmy_ap_norm
	s_cmp_lt_u32 s69, 0x100
	s_cbranch_scc1 .LBB0_1593
	s_movk_i32 s54, 0x100
	s_movk_i32 s55, 0x700
	s_sub_i32 s1, s1, s54
.Lmy_ap_norm:
	s_cmpk_gt_i32 s1, 0x47ff
	s_cbranch_scc1 .LBB0_1593
	v_cndmask_b32_e64 v0, 0, 1, s[22:23]
	v_readlane_b32 s24, v251, 0
	v_readfirstlane_b32 s6, v0
	s_add_i32 s19, s18, s6
	s_and_b64 s[6:7], s[22:23], exec
	v_lshlrev_b32_e32 v0, 2, v2
	s_cselect_b32 s6, 0, 0x4000000
	s_add_u32 s7, s4, 0x14198000
	v_and_b32_e32 v4, 0xfc, v0
	v_and_b32_e32 v0, 64, v199
	s_addc_u32 s14, s5, 0
	v_add_u32_e32 v0, 64, v0
	v_xor_b32_e32 v3, 1, v199
	s_cmp_eq_u32 s19, 0
	v_readlane_b32 s30, v251, 6
	v_readlane_b32 s36, v251, 56
	v_cmp_lt_i32_e32 vcc, v3, v0
	v_readlane_b32 s31, v251, 7
	v_readlane_b32 s37, v251, 57
	v_readlane_b32 s40, v251, 60
	v_readlane_b32 s41, v251, 61
	s_cselect_b32 s18, s36, s30
	v_cndmask_b32_e32 v3, v199, v3, vcc
	s_cselect_b32 s15, s37, s31
	s_cselect_b32 s21, s41, s14
	s_cselect_b32 s24, s40, s7
	s_add_u32 s6, s18, s6
	v_lshlrev_b32_e32 v37, 2, v3
	v_xor_b32_e32 v3, 2, v199
	s_addc_u32 s7, s15, 0
	v_cmp_lt_i32_e32 vcc, v3, v0
	s_and_b64 s[14:15], s[22:23], exec
	s_cselect_b32 s18, 0, 8
	v_cndmask_b32_e32 v3, v199, v3, vcc
	s_lshl_b32 s88, s19, 10
	v_lshlrev_b32_e32 v40, 2, v3
	v_xor_b32_e32 v3, 4, v199
	s_mov_b64 s[52:53], s[22:23]
	v_readlane_b32 s26, v251, 2
	v_readlane_b32 s48, v252, 4
	s_lshl_b64 s[22:23], s[88:89], 2
	v_cmp_lt_i32_e32 vcc, v3, v0
	v_readlane_b32 s27, v251, 3
	v_readlane_b32 s49, v252, 5
	s_add_u32 s26, s48, s22
	v_cndmask_b32_e32 v3, v199, v3, vcc
	s_addc_u32 s27, s49, s23
	v_lshlrev_b32_e32 v41, 2, v3
	v_xor_b32_e32 v3, 8, v199
	s_and_b64 s[22:23], s[52:53], exec
	v_cmp_lt_i32_e32 vcc, v3, v0
	s_mul_i32 s14, s19, 0xcc00
	s_cselect_b32 s19, 0, 0x800000
	v_cndmask_b32_e32 v3, v199, v3, vcc
	s_mov_b32 s15, s89
	s_add_u32 s19, s24, s19
	v_lshlrev_b32_e32 v42, 2, v3
	v_xor_b32_e32 v3, 16, v199
	s_addc_u32 s22, s21, 0
	s_lshl_b64 s[14:15], s[14:15], 2
	v_cmp_lt_i32_e32 vcc, v3, v0
	s_add_u32 s23, s4, s14
	s_addc_u32 s24, s5, s15
	v_cndmask_b32_e32 v3, v199, v3, vcc
	v_lshlrev_b32_e32 v43, 2, v3
	v_xor_b32_e32 v3, 32, v199
	s_ashr_i32 s15, s20, 31
	v_cmp_lt_i32_e32 vcc, v3, v0
	s_add_u32 s14, s69, s20
	v_readlane_b32 s20, v253, 43
	v_cndmask_b32_e32 v0, v199, v3, vcc
	s_addc_u32 s15, s20, s15
	s_sub_u32 s14, s14, s54
	s_subb_u32 s15, s15, 0
	v_lshlrev_b32_e32 v44, 2, v0
	v_lshlrev_b32_e32 v0, 2, v4
	s_lshl_b64 s[14:15], s[14:15], 11
	v_lshl_add_u64 v[26:27], s[26:27], 0, v[0:1]
	v_and_b32_e32 v0, 63, v2
	s_add_u32 s4, s4, s14
	v_readlane_b32 s28, v251, 4
	v_readlane_b32 s29, v251, 5
	v_lshlrev_b32_e32 v0, 3, v0
	s_addc_u32 s5, s5, s15
	v_or_b32_e32 v6, 0x100, v4
	v_or_b32_e32 v8, 0x200, v4
	v_or_b32_e32 v14, 0x300, v4
	v_lshl_add_u64 v[2:3], s[4:5], 0, v[0:1]
	s_mov_b64 s[4:5], 0x46b8000
	v_readlane_b32 s28, v253, 47
	v_lshl_add_u64 v[28:29], v[2:3], 0, s[4:5]
	v_lshlrev_b32_e32 v0, 2, v4
	v_lshlrev_b32_e32 v30, 2, v6
	v_lshlrev_b32_e32 v32, 2, v8
	v_lshlrev_b32_e32 v34, 2, v14
	s_mov_b32 s26, 0x800000
	v_readlane_b32 s29, v253, 48
	s_cmp_eq_u32 s54, 0
	s_cbranch_scc1 .Lmy_ap_st
	s_lshl_b32 s28, s55, 11
.Lmy_ap_st:
	v_readlane_b32 s25, v251, 1
	v_readlane_b32 s38, v251, 58
	v_readlane_b32 s39, v251, 59
	v_readlane_b32 s42, v251, 62
	v_readlane_b32 s43, v251, 63
	v_readlane_b32 s44, v252, 0
	v_readlane_b32 s45, v252, 1
	v_readlane_b32 s46, v252, 2
	v_readlane_b32 s47, v252, 3
	v_readlane_b32 s50, v252, 6
	v_readlane_b32 s51, v252, 7
	s_branch .LBB0_1590
; __device__ __forceinline__ unsigned cvt_pk_bf16(float lo, float hi) { unsigned r; asm volatile("v_cvt_pk_bf16_f32 %0, %1, %2" : "=v"(r) : "v"(lo), "v"(hi)); return r; }
; __global__ void __launch_bounds__(512, 2) fwd_kernel(KArgs a) {
;     ...
;             for (int row = gw; row < MH; row += NGW) {
;                 const bool isc = row >= ML; const int rr = isc ? row - ML : row;
;                 const float* xr = (isc ? xcin : xin) + (size_t)rr * 1024;
;                 const float* md = modl + (size_t)(isc ? 16 : hf * HB + (row >> 11)) * 3072;
;                 const float* ng = a.in[6] + l * 1024;
;                 f32x4 v[4]; float ss = 0.f;
; #pragma unroll
;                 for (int j = 0; j < 4; ++j) { v[j] = *(const f32x4*)(xr + 4 * lane + 256 * j); ss += (v[j][0] * v[j][0] + v[j][1] * v[j][1]) + (v[j][2] * v[j][2] + v[j][3] * v[j][3]); }
;                 const float rinv = rsqrtf(wave_sum(ss) * (1.f / 1024.f) + EPS);
; #pragma unroll
;                 for (int j = 0; j < 4; ++j) { const int c = 4 * lane + 256 * j; const f32x4 gg = *(const f32x4*)(ng + c), sh = *(const f32x4*)(md + c), sc = *(const f32x4*)(md + 1024 + c);
;                     const f32x4 o = v[j] * rinv * gg * (sc + 1.f) + sh; u32x2 w; w.x = cvt_pk_bf16(o[0], o[1]); w.y = cvt_pk_bf16(o[2], o[3]);
;                     *(u32x2*)(HZ + (size_t)row * 1024 + c) = w; }
.LBB0_1589:
	s_add_i32 s25, s1, 0xffffc000
	s_and_b64 s[14:15], exec, s[20:21]
	s_cselect_b32 s14, s25, s1
	s_cselect_b32 s20, s22, s7
	s_cselect_b32 s21, s19, s6
	s_ashr_i32 s15, s14, 31
	s_lshl_b64 s[14:15], s[14:15], 12
	s_add_u32 s14, s21, s14
	s_addc_u32 s15, s20, s15
	v_lshl_add_u64 v[2:3], s[14:15], 0, v[0:1]
	flat_load_dwordx4 v[18:21], v[2:3]
	flat_load_dwordx4 v[14:17], v[2:3] offset:1024
	s_lshl_b64 s[4:5], s[4:5], 2
	s_add_u32 s20, s23, s4
	s_addc_u32 s21, s24, s5
	s_add_u32 s4, s20, 0x1000
	s_addc_u32 s5, s21, 0
	v_lshl_add_u64 v[50:51], s[4:5], 0, v[0:1]
	s_add_i32 s1, s1, s55
	s_cmpk_lt_i32 s1, 0x4800
	s_waitcnt vmcnt(0) lgkmcnt(0)
	v_pk_mul_f32 v[4:5], v[20:21], v[20:21]
	v_pk_mul_f32 v[6:7], v[18:19], v[18:19]
	s_nop 0
	v_pk_mov_b32 v[8:9], v[6:7], v[4:5] op_sel:[1,0]
	v_mov_b32_e32 v7, v5
	v_pk_add_f32 v[22:23], v[8:9], v[6:7]
	v_pk_mul_f32 v[4:5], v[16:17], v[16:17]
	v_pk_mul_f32 v[6:7], v[14:15], v[14:15]
	v_pk_add_f32 v[22:23], v[22:23], v[22:23] op_sel:[0,1] op_sel_hi:[1,0]
	v_pk_mov_b32 v[8:9], v[6:7], v[4:5] op_sel:[1,0]
	v_mov_b32_e32 v7, v5
	v_pk_add_f32 v[24:25], v[8:9], v[6:7]
	flat_load_dwordx4 v[6:9], v[2:3] offset:2048
	s_nop 0
	flat_load_dwordx4 v[2:5], v[2:3] offset:3072
	v_pk_add_f32 v[24:25], v[24:25], v[24:25] op_sel:[0,1] op_sel_hi:[1,0]
	flat_load_dwordx4 v[50:53], v[50:51]
	s_waitcnt vmcnt(0) lgkmcnt(0)
	v_mul_f32_e32 v36, v9, v9
	v_mul_f32_e32 v31, v2, v2
	v_mul_f32_e32 v33, v3, v3
	v_mov_b32_e32 v23, v31
	v_mov_b32_e32 v25, v33
	v_pk_add_f32 v[22:23], v[22:23], v[24:25]
	v_mul_f32_e32 v24, v7, v7
	v_mul_f32_e32 v35, v4, v4
	v_mul_f32_e32 v45, v5, v5
	v_pk_fma_f32 v[24:25], v[6:7], v[6:7], v[24:25] op_sel_hi:[1,1,0]
	v_pk_fma_f32 v[38:39], v[8:9], v[8:9], v[36:37] op_sel_hi:[1,1,0]
	v_mov_b32_e32 v25, v35
	v_mov_b32_e32 v39, v45
	v_pk_add_f32 v[24:25], v[24:25], v[38:39]
	v_lshl_add_u64 v[38:39], s[20:21], 0, v[0:1]
	v_pk_add_f32 v[22:23], v[22:23], v[24:25]
	flat_load_dwordx4 v[46:49], v[38:39]
	v_add_f32_e32 v22, v22, v23
	ds_bpermute_b32 v23, v37, v22
	v_mov_b32_e32 v31, v1
	v_mov_b32_e32 v33, v1
	v_mov_b32_e32 v35, v1
	s_waitcnt lgkmcnt(0)
	v_add_f32_e32 v22, v22, v23
	ds_bpermute_b32 v23, v40, v22
	s_waitcnt lgkmcnt(0)
	v_add_f32_e32 v22, v22, v23
	ds_bpermute_b32 v23, v41, v22
	s_waitcnt lgkmcnt(0)
	v_add_f32_e32 v22, v22, v23
	ds_bpermute_b32 v23, v42, v22
	s_waitcnt lgkmcnt(0)
	v_add_f32_e32 v22, v22, v23
	ds_bpermute_b32 v23, v43, v22
	s_waitcnt lgkmcnt(0)
	v_add_f32_e32 v22, v22, v23
	ds_bpermute_b32 v23, v44, v22
	s_waitcnt lgkmcnt(0)
	v_add_f32_e32 v22, v22, v23
	v_fmamk_f32 v22, v22, 0x3a800000, v197
	v_cmp_gt_f32_e32 vcc, s26, v22
	v_mul_f32_e32 v23, 0x4b800000, v22
	s_nop 0
	v_cndmask_b32_e32 v22, v22, v23, vcc
	v_rsq_f32_e32 v22, v22
	s_nop 0
	v_mul_f32_e32 v23, 0x45800000, v22
	v_cndmask_b32_e32 v36, v22, v23, vcc
	global_load_dwordx4 v[22:25], v[26:27], off
	v_pk_mul_f32 v[20:21], v[36:37], v[20:21] op_sel_hi:[0,1]
	v_pk_mul_f32 v[18:19], v[36:37], v[18:19] op_sel_hi:[0,1]
	v_pk_mul_f32 v[16:17], v[36:37], v[16:17] op_sel_hi:[0,1]
	v_pk_mul_f32 v[14:15], v[36:37], v[14:15] op_sel_hi:[0,1]
	v_pk_mul_f32 v[8:9], v[36:37], v[8:9] op_sel_hi:[0,1]
	v_pk_mul_f32 v[6:7], v[36:37], v[6:7] op_sel_hi:[0,1]
	v_pk_mul_f32 v[4:5], v[36:37], v[4:5] op_sel_hi:[0,1]
	v_pk_mul_f32 v[2:3], v[36:37], v[2:3] op_sel_hi:[0,1]
	s_waitcnt vmcnt(0)
	v_pk_mul_f32 v[18:19], v[22:23], v[18:19]
	v_pk_mul_f32 v[20:21], v[24:25], v[20:21]
	v_pk_add_f32 v[24:25], v[50:51], 1.0 op_sel_hi:[1,0]
	v_pk_add_f32 v[22:23], v[52:53], 1.0 op_sel_hi:[1,0]
	v_pk_fma_f32 v[18:19], v[24:25], v[18:19], v[46:47]
	v_pk_fma_f32 v[20:21], v[22:23], v[20:21], v[48:49]
	v_cvt_pk_bf16_f32 v18, v18, v19
	v_lshl_add_u64 v[46:47], s[4:5], 0, v[30:31]
	v_cvt_pk_bf16_f32 v19, v20, v21
	flat_store_dwordx2 v[28:29], v[18:19]
	global_load_dwordx4 v[22:25], v[26:27], off offset:1024
	s_nop 0
	flat_load_dwordx4 v[18:21], v[38:39] offset:1024
	s_waitcnt vmcnt(0)
	v_pk_mul_f32 v[14:15], v[22:23], v[14:15]
	flat_load_dwordx4 v[46:49], v[46:47]
	v_pk_mul_f32 v[16:17], v[24:25], v[16:17]
	s_waitcnt vmcnt(0) lgkmcnt(0)
	v_pk_add_f32 v[24:25], v[46:47], 1.0 op_sel_hi:[1,0]
	v_pk_add_f32 v[22:23], v[48:49], 1.0 op_sel_hi:[1,0]
	v_pk_fma_f32 v[14:15], v[24:25], v[14:15], v[18:19]
	v_pk_fma_f32 v[16:17], v[22:23], v[16:17], v[20:21]
	v_cvt_pk_bf16_f32 v14, v14, v15
	v_lshl_add_u64 v[22:23], s[4:5], 0, v[32:33]
	v_cvt_pk_bf16_f32 v15, v16, v17
	flat_store_dwordx2 v[28:29], v[14:15] offset:512
	global_load_dwordx4 v[14:17], v[26:27], off offset:2048
	s_nop 0
	flat_load_dwordx4 v[18:21], v[38:39] offset:2048
	s_waitcnt vmcnt(0)
	v_pk_mul_f32 v[6:7], v[14:15], v[6:7]
	flat_load_dwordx4 v[22:25], v[22:23]
	v_pk_mul_f32 v[8:9], v[16:17], v[8:9]
	s_waitcnt vmcnt(0) lgkmcnt(0)
	v_pk_add_f32 v[16:17], v[22:23], 1.0 op_sel_hi:[1,0]
	v_pk_add_f32 v[14:15], v[24:25], 1.0 op_sel_hi:[1,0]
	v_pk_fma_f32 v[6:7], v[16:17], v[6:7], v[18:19]
	v_pk_fma_f32 v[8:9], v[14:15], v[8:9], v[20:21]
	v_cvt_pk_bf16_f32 v6, v6, v7
	v_lshl_add_u64 v[18:19], s[4:5], 0, v[34:35]
	v_cvt_pk_bf16_f32 v7, v8, v9
	flat_store_dwordx2 v[28:29], v[6:7] offset:1024
	global_load_dwordx4 v[6:9], v[26:27], off offset:3072
	s_nop 0
	flat_load_dwordx4 v[14:17], v[38:39] offset:3072
	s_waitcnt vmcnt(0)
	v_pk_mul_f32 v[2:3], v[6:7], v[2:3]
	flat_load_dwordx4 v[18:21], v[18:19]
	v_pk_mul_f32 v[4:5], v[8:9], v[4:5]
	s_waitcnt vmcnt(0) lgkmcnt(0)
	v_pk_add_f32 v[8:9], v[18:19], 1.0 op_sel_hi:[1,0]
	v_pk_add_f32 v[6:7], v[20:21], 1.0 op_sel_hi:[1,0]
	v_pk_fma_f32 v[2:3], v[8:9], v[2:3], v[14:15]
	v_pk_fma_f32 v[4:5], v[6:7], v[4:5], v[16:17]
	v_cvt_pk_bf16_f32 v2, v2, v3
	s_nop 0
	v_cvt_pk_bf16_f32 v3, v4, v5
	flat_store_dwordx2 v[28:29], v[2:3] offset:1536
	v_lshl_add_u64 v[28:29], v[28:29], 0, s[28:29]
	s_cbranch_scc0 .LBB0_1592

; #define GSYNC() xcd_barrier(xbar)
; __device__ __forceinline__ void xcd_barrier(const XcdBarrier& b) {
;     asm volatile("s_waitcnt vmcnt(0)" ::: "memory");
;     __syncthreads();
;     if (threadIdx.x == 0) {
;         unsigned* bar = b.bar;
;         __builtin_amdgcn_s_waitcnt(0);
; __global__ void __launch_bounds__(512, 2) fwd_kernel(KArgs a) {
;     ...
;             } }
;             }
;             } }
;             }
;             GSYNC();
.LBB0_1592:
	v_readlane_b32 s28, v252, 10
	v_readlane_b32 s30, v252, 12
	v_readlane_b32 s29, v252, 11
	v_readlane_b32 s31, v252, 13
	s_branch .Lmy_pad_LBB01593
	s_nop 0
	s_nop 0
	s_nop 0
	s_nop 0
	s_nop 0
	s_nop 0
	s_nop 0
	s_nop 0
	s_nop 0
	s_nop 0
	s_nop 0
	s_nop 0
	s_nop 0
.Lmy_pad_LBB01593:
.LBB0_1593:
	s_waitcnt vmcnt(0)
	s_waitcnt lgkmcnt(0)
	s_barrier
	s_and_saveexec_b64 s[4:5], s[96:97]
	s_cbranch_execnz .LBB0_1594
	s_getpc_b64 s[98:99]
